# speedup vs baseline: 1.0034x; 1.0008x over previous
;   #define LDA(dst,b,h) for(int m=0;m<4;++m)for(int k=0;k<2;++k) \
;     dst[m][k]=*reinterpret_cast<const bf16x8*>((char*)SA(b,h)+lds_byte(wr*64+m*16+fr,k*32+fq*8))
;   #define LDB(dst,b,h) for(int n=0;n<2;++n)for(int k=0;k<2;++k) \
;     dst[n][k]=*reinterpret_cast<const bf16x8*>((char*)SB(b,h)+lds_byte(wc*32+n*16+fr,k*32+fq*8))
;   #define MMA(ai,bj,At,Bt_) do{__builtin_amdgcn_s_setprio(1); \
;     for(int m=0;m<4;++m)for(int n=0;n<2;++n)for(int k=0;k<2;++k) \
;       acc[ai][bj][m][n]=__builtin_amdgcn_mfma_f32_16x16x32_bf16(Bt_[n][k],At[m][k],acc[ai][bj][m][n],0,0,0); \
;     __builtin_amdgcn_s_setprio(0);}while(0)
;   #define WAIT_L(n) asm volatile("s_waitcnt lgkmcnt(" #n ")":::"memory")
;   #define BAR __builtin_amdgcn_s_barrier()
;   #define SCHED __builtin_amdgcn_sched_barrier(0)
; template <bool TWO, class MID> ...
;     ...
;     LDB(B0,0,0); SCHED; LDA(At,0,0); STAGE_A(SA(1,1),1,t+1);
;     WAIT_L(8); BAR; WAIT_L(0); MMA(0,0,At,B0); BAR; SCHED;
;     LDB(B1,0,1); STAGE_B(SB(0,0),0,t+2);
;     BAR; WAIT_L(0); MMA(0,1,At,B1); BAR;
;     LDA(At,0,1); STAGE_A(SA(0,0),0,t+2);
;     BAR; WAIT_L(0); MMA(1,0,At,B0); BAR; SCHED;
;     STAGE_B(SB(0,1),1,t+2);
.LBB0_405:
	ds_read_b128 v[130:133], v219
	ds_read_b128 v[134:137], v219 offset:1024
	ds_read_b128 v[138:141], v219 offset:2048
	ds_read_b128 v[142:145], v219 offset:3072
	ds_read_b128 v[186:189], v211
	ds_read_b128 v[190:193], v211 offset:1024
	ds_read_b128 v[178:181], v209
	ds_read_b128 v[182:185], v209 offset:1024
	ds_read_b128 v[170:173], v207
	ds_read_b128 v[174:177], v207 offset:1024
	ds_read_b128 v[162:165], v205
	ds_read_b128 v[166:169], v205 offset:1024
	s_cmp_lt_u32 s26, 8
	s_mov_b64 s[14:15], -1
	s_cbranch_scc0 .LBB0_407
	s_add_u32 s14, s1, s12
	s_addc_u32 s15, s5, s13
	s_add_u32 s14, s14, 0x10120080
	s_addc_u32 s15, s15, 0
	s_add_u32 m0, s98, 0xc000
	global_load_lds_dwordx4 v196, s[14:15]
	s_add_u32 m0, s98, 0xe000
	global_load_lds_dwordx4 v198, s[14:15]
	s_mov_b64 s[14:15], 0
.LBB0_407:
	s_andn2_b64 vcc, exec, s[14:15]
	s_cbranch_vccnz .LBB0_409
	s_add_i32 s62, s26, -7
	s_lshl_b64 s[14:15], s[62:63], 7
	s_add_u32 s14, s20, s14
	s_addc_u32 s15, s21, s15
	s_add_u32 s14, s14, 0xc0000
	s_addc_u32 s15, s15, 0
	s_add_u32 m0, s98, 0xc000
	global_load_lds_dwordx4 v224, s[14:15]
	s_add_u32 m0, s98, 0xe000
	global_load_lds_dwordx4 v222, s[14:15]
.LBB0_409:
	s_waitcnt lgkmcnt(8)
	s_setprio 1
	s_barrier
	s_waitcnt lgkmcnt(0)
	v_mfma_f32_16x16x32_bf16 v[126:129], v[130:133], v[186:189], v[126:129]
	v_mfma_f32_16x16x32_bf16 v[122:125], v[138:141], v[186:189], v[122:125]
	v_mfma_f32_16x16x32_bf16 v[118:121], v[130:133], v[178:181], v[118:121]
	v_mfma_f32_16x16x32_bf16 v[114:117], v[138:141], v[178:181], v[114:117]
	v_mfma_f32_16x16x32_bf16 v[110:113], v[130:133], v[170:173], v[110:113]
	v_mfma_f32_16x16x32_bf16 v[106:109], v[138:141], v[170:173], v[106:109]
	v_mfma_f32_16x16x32_bf16 v[102:105], v[130:133], v[162:165], v[102:105]
	v_mfma_f32_16x16x32_bf16 v[98:101], v[138:141], v[162:165], v[98:101]
	v_mfma_f32_16x16x32_bf16 v[126:129], v[134:137], v[190:193], v[126:129]
	v_mfma_f32_16x16x32_bf16 v[122:125], v[142:145], v[190:193], v[122:125]
	v_mfma_f32_16x16x32_bf16 v[118:121], v[134:137], v[182:185], v[118:121]
	v_mfma_f32_16x16x32_bf16 v[114:117], v[142:145], v[182:185], v[114:117]
	v_mfma_f32_16x16x32_bf16 v[110:113], v[134:137], v[174:177], v[110:113]
	v_mfma_f32_16x16x32_bf16 v[106:109], v[142:145], v[174:177], v[106:109]
	v_mfma_f32_16x16x32_bf16 v[102:105], v[134:137], v[166:169], v[102:105]
	v_mfma_f32_16x16x32_bf16 v[98:101], v[142:145], v[166:169], v[98:101]
	s_barrier
	s_setprio 0
	ds_read_b128 v[146:149], v217
	ds_read_b128 v[150:153], v217 offset:1024
	ds_read_b128 v[154:157], v217 offset:2048
	ds_read_b128 v[158:161], v217 offset:3072
	s_cmp_lt_u32 s26, 6
	s_cselect_b64 s[14:15], -1, 0
	s_mov_b64 s[16:17], -1
	s_and_b64 vcc, exec, s[14:15]
	s_cbranch_vccz .LBB0_411
	s_add_u32 s16, s24, s12
	s_addc_u32 s17, s25, s13
	s_add_u32 s16, s16, 0x2e00100
	s_addc_u32 s17, s17, 0
	s_add_u32 m0, s98, 0x10000
	global_load_lds_dwordx4 v200, s[16:17]
	s_add_u32 m0, s98, 0x12000
	global_load_lds_dwordx4 v202, s[16:17]
	s_mov_b64 s[16:17], 0
.LBB0_411:
	s_andn2_b64 vcc, exec, s[16:17]
	s_cbranch_vccnz .LBB0_413
	s_add_i32 s62, s26, -6
	s_lshl_b64 s[16:17], s[62:63], 7
	s_add_u32 s16, s22, s16
	s_addc_u32 s17, s23, s17
	s_add_u32 m0, s98, 0x10000
	global_load_lds_dwordx4 v232, s[16:17]
	s_add_u32 m0, s98, 0x12000
	global_load_lds_dwordx4 v234, s[16:17]
.LBB0_413:
	s_setprio 1
	s_barrier
	s_waitcnt lgkmcnt(0)
	v_mfma_f32_16x16x32_bf16 v[94:97], v[146:149], v[186:189], v[94:97]
	v_mfma_f32_16x16x32_bf16 v[90:93], v[154:157], v[186:189], v[90:93]
	v_mfma_f32_16x16x32_bf16 v[86:89], v[146:149], v[178:181], v[86:89]
	v_mfma_f32_16x16x32_bf16 v[82:85], v[154:157], v[178:181], v[82:85]
	v_mfma_f32_16x16x32_bf16 v[78:81], v[146:149], v[170:173], v[78:81]
	v_mfma_f32_16x16x32_bf16 v[74:77], v[154:157], v[170:173], v[74:77]
	v_mfma_f32_16x16x32_bf16 v[70:73], v[146:149], v[162:165], v[70:73]
	v_mfma_f32_16x16x32_bf16 v[66:69], v[154:157], v[162:165], v[66:69]
	v_mfma_f32_16x16x32_bf16 v[94:97], v[150:153], v[190:193], v[94:97]
	v_mfma_f32_16x16x32_bf16 v[90:93], v[158:161], v[190:193], v[90:93]
	v_mfma_f32_16x16x32_bf16 v[86:89], v[150:153], v[182:185], v[86:89]
	v_mfma_f32_16x16x32_bf16 v[82:85], v[158:161], v[182:185], v[82:85]
	v_mfma_f32_16x16x32_bf16 v[78:81], v[150:153], v[174:177], v[78:81]
	v_mfma_f32_16x16x32_bf16 v[74:77], v[158:161], v[174:177], v[74:77]
	v_mfma_f32_16x16x32_bf16 v[70:73], v[150:153], v[166:169], v[70:73]
	v_mfma_f32_16x16x32_bf16 v[66:69], v[158:161], v[166:169], v[66:69]
	s_barrier
	s_setprio 0
	ds_read_b128 v[186:189], v211 offset:16384
	ds_read_b128 v[190:193], v211 offset:17408
	ds_read_b128 v[178:181], v209 offset:16384
	ds_read_b128 v[182:185], v209 offset:17408
	ds_read_b128 v[170:173], v207 offset:16384
	ds_read_b128 v[174:177], v207 offset:17408
	ds_read_b128 v[162:165], v205 offset:16384
	ds_read_b128 v[166:169], v205 offset:17408
	s_mov_b64 s[16:17], -1
	s_and_b64 vcc, exec, s[14:15]
	s_cbranch_vccz .LBB0_415
	s_add_u32 s16, s1, s12
	s_addc_u32 s17, s5, s13
	s_add_u32 s16, s16, 0x10000100
	s_addc_u32 s17, s17, 0
	s_add_u32 m0, s98, 0x0
	global_load_lds_dwordx4 v196, s[16:17]
	s_add_u32 m0, s98, 0x2000
	global_load_lds_dwordx4 v198, s[16:17]
	s_mov_b64 s[16:17], 0
.LBB0_415:
	s_andn2_b64 vcc, exec, s[16:17]
	s_cbranch_vccnz .LBB0_417
	s_add_i32 s62, s26, -6
	s_lshl_b64 s[16:17], s[62:63], 7
	s_add_u32 s16, s20, s16
	s_addc_u32 s17, s21, s17
	s_add_u32 m0, s98, 0x0
	global_load_lds_dwordx4 v224, s[16:17]
	s_add_u32 m0, s98, 0x2000
	global_load_lds_dwordx4 v222, s[16:17]
;   #define LDA(dst,b,h) for(int m=0;m<4;++m)for(int k=0;k<2;++k) \
;     dst[m][k]=*reinterpret_cast<const bf16x8*>((char*)SA(b,h)+lds_byte(wr*64+m*16+fr,k*32+fq*8))
;   #define LDB(dst,b,h) for(int n=0;n<2;++n)for(int k=0;k<2;++k) \
;     dst[n][k]=*reinterpret_cast<const bf16x8*>((char*)SB(b,h)+lds_byte(wc*32+n*16+fr,k*32+fq*8))
;   #define MMA(ai,bj,At,Bt_) do{__builtin_amdgcn_s_setprio(1); \
;     for(int m=0;m<4;++m)for(int n=0;n<2;++n)for(int k=0;k<2;++k) \
;       acc[ai][bj][m][n]=__builtin_amdgcn_mfma_f32_16x16x32_bf16(Bt_[n][k],At[m][k],acc[ai][bj][m][n],0,0,0); \
;     __builtin_amdgcn_s_setprio(0);}while(0)
;   #define WAIT_V(n) asm volatile("s_waitcnt vmcnt(" #n ")":::"memory")
;   #define WAIT_L(n) asm volatile("s_waitcnt lgkmcnt(" #n ")":::"memory")
;   #define BAR __builtin_amdgcn_s_barrier()
;   #define SCHED __builtin_amdgcn_sched_barrier(0)
; template <bool TWO, class MID> ...
;     ...
;     BAR; WAIT_L(0); MMA(1,0,At,B0); BAR; SCHED;
;     STAGE_B(SB(0,1),1,t+2);
;     WAIT_V(6); BAR; MMA(1,1,At,B1); BAR;
;     LDB(B0,1,0); SCHED; LDA(At,1,0); STAGE_A(SA(0,1),1,t+2);
;     WAIT_L(8); BAR; WAIT_L(0); MMA(0,0,At,B0); BAR; SCHED;
;     LDB(B1,1,1); STAGE_B(SB(1,0),0,t+3);
.LBB0_417:
	s_setprio 1
	s_barrier
	s_waitcnt lgkmcnt(0)
	v_mfma_f32_16x16x32_bf16 v[62:65], v[130:133], v[186:189], v[62:65]
	v_mfma_f32_16x16x32_bf16 v[58:61], v[138:141], v[186:189], v[58:61]
	v_mfma_f32_16x16x32_bf16 v[54:57], v[130:133], v[178:181], v[54:57]
	v_mfma_f32_16x16x32_bf16 v[50:53], v[138:141], v[178:181], v[50:53]
	v_mfma_f32_16x16x32_bf16 v[46:49], v[130:133], v[170:173], v[46:49]
	v_mfma_f32_16x16x32_bf16 v[42:45], v[138:141], v[170:173], v[42:45]
	v_mfma_f32_16x16x32_bf16 v[38:41], v[130:133], v[162:165], v[38:41]
	v_mfma_f32_16x16x32_bf16 v[34:37], v[138:141], v[162:165], v[34:37]
	v_mfma_f32_16x16x32_bf16 v[62:65], v[134:137], v[190:193], v[62:65]
	v_mfma_f32_16x16x32_bf16 v[58:61], v[142:145], v[190:193], v[58:61]
	v_mfma_f32_16x16x32_bf16 v[54:57], v[134:137], v[182:185], v[54:57]
	v_mfma_f32_16x16x32_bf16 v[50:53], v[142:145], v[182:185], v[50:53]
	v_mfma_f32_16x16x32_bf16 v[46:49], v[134:137], v[174:177], v[46:49]
	v_mfma_f32_16x16x32_bf16 v[42:45], v[142:145], v[174:177], v[42:45]
	v_mfma_f32_16x16x32_bf16 v[38:41], v[134:137], v[166:169], v[38:41]
	v_mfma_f32_16x16x32_bf16 v[34:37], v[142:145], v[166:169], v[34:37]
	s_barrier
	s_setprio 0
	s_mov_b64 s[16:17], -1
	s_and_b64 vcc, exec, s[14:15]
	s_cbranch_vccz .LBB0_419
	s_add_u32 s16, s24, s12
	s_addc_u32 s17, s25, s13
	s_add_u32 s16, s16, 0x2e20100
	s_addc_u32 s17, s17, 0
	s_add_u32 m0, s98, 0x14000
	global_load_lds_dwordx4 v200, s[16:17]
	s_add_u32 m0, s98, 0x16000
	global_load_lds_dwordx4 v202, s[16:17]
	s_mov_b64 s[16:17], 0
.LBB0_419:
	s_andn2_b64 vcc, exec, s[16:17]
	s_cbranch_vccnz .LBB0_421
	s_add_i32 s62, s26, -6
	s_lshl_b64 s[16:17], s[62:63], 7
	s_add_u32 s16, s22, s16
	s_addc_u32 s17, s23, s17
	s_add_u32 s16, s16, 0x40000
	s_addc_u32 s17, s17, 0
	s_add_u32 m0, s98, 0x14000
	global_load_lds_dwordx4 v232, s[16:17]
	s_add_u32 m0, s98, 0x16000
	global_load_lds_dwordx4 v234, s[16:17]
.LBB0_421:
	s_waitcnt vmcnt(6)
	s_setprio 1
	s_barrier
	v_mfma_f32_16x16x32_bf16 v[30:33], v[146:149], v[186:189], v[30:33]
	v_mfma_f32_16x16x32_bf16 v[26:29], v[154:157], v[186:189], v[26:29]
	v_mfma_f32_16x16x32_bf16 v[22:25], v[146:149], v[178:181], v[22:25]
	v_mfma_f32_16x16x32_bf16 v[18:21], v[154:157], v[178:181], v[18:21]
	v_mfma_f32_16x16x32_bf16 v[14:17], v[146:149], v[170:173], v[14:17]
	v_mfma_f32_16x16x32_bf16 v[10:13], v[154:157], v[170:173], v[10:13]
	v_mfma_f32_16x16x32_bf16 v[6:9], v[146:149], v[162:165], v[6:9]
	v_mfma_f32_16x16x32_bf16 v[2:5], v[154:157], v[162:165], v[2:5]
	v_mfma_f32_16x16x32_bf16 v[30:33], v[150:153], v[190:193], v[30:33]
	v_mfma_f32_16x16x32_bf16 v[26:29], v[158:161], v[190:193], v[26:29]
	v_mfma_f32_16x16x32_bf16 v[22:25], v[150:153], v[182:185], v[22:25]
	v_mfma_f32_16x16x32_bf16 v[18:21], v[158:161], v[182:185], v[18:21]
	v_mfma_f32_16x16x32_bf16 v[14:17], v[150:153], v[174:177], v[14:17]
	v_mfma_f32_16x16x32_bf16 v[10:13], v[158:161], v[174:177], v[10:13]
	v_mfma_f32_16x16x32_bf16 v[6:9], v[150:153], v[166:169], v[6:9]
	v_mfma_f32_16x16x32_bf16 v[2:5], v[158:161], v[166:169], v[2:5]
	s_barrier
	s_setprio 0
	ds_read_b128 v[130:133], v215
	ds_read_b128 v[134:137], v215 offset:1024
	ds_read_b128 v[138:141], v215 offset:2048
	ds_read_b128 v[142:145], v215 offset:3072
	ds_read_b128 v[186:189], v211 offset:32768
	ds_read_b128 v[190:193], v211 offset:33792
	ds_read_b128 v[178:181], v209 offset:32768
	ds_read_b128 v[182:185], v209 offset:33792
	ds_read_b128 v[170:173], v207 offset:32768
	ds_read_b128 v[174:177], v207 offset:33792
	ds_read_b128 v[162:165], v205 offset:32768
	ds_read_b128 v[166:169], v205 offset:33792
	s_mov_b64 s[16:17], -1
	s_and_b64 vcc, exec, s[14:15]
	s_cbranch_vccz .LBB0_423
	s_add_u32 s14, s1, s12
	s_addc_u32 s15, s5, s13
	s_add_u32 s14, s14, 0x10120100
	s_addc_u32 s15, s15, 0
	s_add_u32 m0, s98, 0x4000
	global_load_lds_dwordx4 v196, s[14:15]
	s_add_u32 m0, s98, 0x6000
	global_load_lds_dwordx4 v198, s[14:15]
	s_mov_b64 s[16:17], 0
.LBB0_423:
	s_andn2_b64 vcc, exec, s[16:17]
	s_cbranch_vccnz .LBB0_425
	s_add_i32 s62, s26, -6
	s_lshl_b64 s[14:15], s[62:63], 7
	s_add_u32 s14, s20, s14
	s_addc_u32 s15, s21, s15
	s_add_u32 s14, s14, 0xc0000
	s_addc_u32 s15, s15, 0
	s_add_u32 m0, s98, 0x4000
	global_load_lds_dwordx4 v224, s[14:15]
	s_add_u32 m0, s98, 0x6000
	global_load_lds_dwordx4 v222, s[14:15]
.LBB0_425:
	s_waitcnt lgkmcnt(8)
	s_setprio 1
	s_barrier
	s_waitcnt lgkmcnt(0)
	v_mfma_f32_16x16x32_bf16 v[126:129], v[130:133], v[186:189], v[126:129]
	v_mfma_f32_16x16x32_bf16 v[122:125], v[138:141], v[186:189], v[122:125]
	v_mfma_f32_16x16x32_bf16 v[118:121], v[130:133], v[178:181], v[118:121]
	v_mfma_f32_16x16x32_bf16 v[114:117], v[138:141], v[178:181], v[114:117]
	v_mfma_f32_16x16x32_bf16 v[110:113], v[130:133], v[170:173], v[110:113]
	v_mfma_f32_16x16x32_bf16 v[106:109], v[138:141], v[170:173], v[106:109]
	v_mfma_f32_16x16x32_bf16 v[102:105], v[130:133], v[162:165], v[102:105]
	v_mfma_f32_16x16x32_bf16 v[98:101], v[138:141], v[162:165], v[98:101]
	v_mfma_f32_16x16x32_bf16 v[126:129], v[134:137], v[190:193], v[126:129]
	v_mfma_f32_16x16x32_bf16 v[122:125], v[142:145], v[190:193], v[122:125]
	v_mfma_f32_16x16x32_bf16 v[118:121], v[134:137], v[182:185], v[118:121]
	v_mfma_f32_16x16x32_bf16 v[114:117], v[142:145], v[182:185], v[114:117]
	v_mfma_f32_16x16x32_bf16 v[110:113], v[134:137], v[174:177], v[110:113]
	v_mfma_f32_16x16x32_bf16 v[106:109], v[142:145], v[174:177], v[106:109]
	v_mfma_f32_16x16x32_bf16 v[102:105], v[134:137], v[166:169], v[102:105]
	v_mfma_f32_16x16x32_bf16 v[98:101], v[142:145], v[166:169], v[98:101]
	s_barrier
	s_setprio 0
	ds_read_b128 v[146:149], v213
	ds_read_b128 v[150:153], v213 offset:1024
	ds_read_b128 v[154:157], v213 offset:2048
	ds_read_b128 v[158:161], v213 offset:3072
	s_cmp_lt_u32 s26, 5
	s_cselect_b64 s[14:15], -1, 0
	s_mov_b64 s[16:17], -1
	s_and_b64 vcc, exec, s[14:15]
	s_cbranch_vccz .LBB0_427
	s_add_u32 s16, s24, s12
	s_addc_u32 s17, s25, s13
	s_add_u32 s16, s16, 0x2e00180
	s_addc_u32 s17, s17, 0
	s_add_u32 m0, s98, 0x18000
	global_load_lds_dwordx4 v200, s[16:17]
	s_add_u32 m0, s98, 0x1a000
	global_load_lds_dwordx4 v202, s[16:17]
	s_mov_b64 s[16:17], 0
;   #define LDA(dst,b,h) for(int m=0;m<4;++m)for(int k=0;k<2;++k) \
;     dst[m][k]=*reinterpret_cast<const bf16x8*>((char*)SA(b,h)+lds_byte(wr*64+m*16+fr,k*32+fq*8))
;   #define LDB(dst,b,h) for(int n=0;n<2;++n)for(int k=0;k<2;++k) \
;     dst[n][k]=*reinterpret_cast<const bf16x8*>((char*)SB(b,h)+lds_byte(wc*32+n*16+fr,k*32+fq*8))
;   #define MMA(ai,bj,At,Bt_) do{__builtin_amdgcn_s_setprio(1); \
;     for(int m=0;m<4;++m)for(int n=0;n<2;++n)for(int k=0;k<2;++k) \
;       acc[ai][bj][m][n]=__builtin_amdgcn_mfma_f32_16x16x32_bf16(Bt_[n][k],At[m][k],acc[ai][bj][m][n],0,0,0); \
;     __builtin_amdgcn_s_setprio(0);}while(0)
;   #define WAIT_L(n) asm volatile("s_waitcnt lgkmcnt(" #n ")":::"memory")
;   #define BAR __builtin_amdgcn_s_barrier()
;   #define SCHED __builtin_amdgcn_sched_barrier(0)
; template <bool TWO, class MID> ...
;     ...
;     LDB(B1,1,1); STAGE_B(SB(1,0),0,t+3);
;     BAR; WAIT_L(0); MMA(0,1,At,B1); BAR;
;     LDA(At,1,1); STAGE_A(SA(1,0),0,t+3);
;     BAR; WAIT_L(0); MMA(1,0,At,B0); BAR; SCHED;
;     STAGE_B(SB(1,1),1,t+3);
.LBB0_427:
	s_andn2_b64 vcc, exec, s[16:17]
	s_cbranch_vccnz .LBB0_429
	s_add_i32 s62, s26, -5
	s_lshl_b64 s[16:17], s[62:63], 7
	s_add_u32 s16, s22, s16
	s_addc_u32 s17, s23, s17
	s_add_u32 m0, s98, 0x18000
	global_load_lds_dwordx4 v232, s[16:17]
	s_add_u32 m0, s98, 0x1a000
	global_load_lds_dwordx4 v234, s[16:17]
.LBB0_429:
	s_setprio 1
	s_barrier
	s_waitcnt lgkmcnt(0)
	v_mfma_f32_16x16x32_bf16 v[94:97], v[146:149], v[186:189], v[94:97]
	v_mfma_f32_16x16x32_bf16 v[90:93], v[154:157], v[186:189], v[90:93]
	v_mfma_f32_16x16x32_bf16 v[86:89], v[146:149], v[178:181], v[86:89]
	v_mfma_f32_16x16x32_bf16 v[82:85], v[154:157], v[178:181], v[82:85]
	v_mfma_f32_16x16x32_bf16 v[78:81], v[146:149], v[170:173], v[78:81]
	v_mfma_f32_16x16x32_bf16 v[74:77], v[154:157], v[170:173], v[74:77]
	v_mfma_f32_16x16x32_bf16 v[70:73], v[146:149], v[162:165], v[70:73]
	v_mfma_f32_16x16x32_bf16 v[66:69], v[154:157], v[162:165], v[66:69]
	v_mfma_f32_16x16x32_bf16 v[94:97], v[150:153], v[190:193], v[94:97]
	v_mfma_f32_16x16x32_bf16 v[90:93], v[158:161], v[190:193], v[90:93]
	v_mfma_f32_16x16x32_bf16 v[86:89], v[150:153], v[182:185], v[86:89]
	v_mfma_f32_16x16x32_bf16 v[82:85], v[158:161], v[182:185], v[82:85]
	v_mfma_f32_16x16x32_bf16 v[78:81], v[150:153], v[174:177], v[78:81]
	v_mfma_f32_16x16x32_bf16 v[74:77], v[158:161], v[174:177], v[74:77]
	v_mfma_f32_16x16x32_bf16 v[70:73], v[150:153], v[166:169], v[70:73]
	v_mfma_f32_16x16x32_bf16 v[66:69], v[158:161], v[166:169], v[66:69]
	s_barrier
	s_setprio 0
	ds_read_b128 v[186:189], v211 offset:49152
	ds_read_b128 v[190:193], v211 offset:50176
	ds_read_b128 v[178:181], v209 offset:49152
	ds_read_b128 v[182:185], v209 offset:50176
	ds_read_b128 v[170:173], v207 offset:49152
	ds_read_b128 v[174:177], v207 offset:50176
	ds_read_b128 v[162:165], v205 offset:49152
	ds_read_b128 v[166:169], v205 offset:50176
	s_mov_b64 s[16:17], -1
	s_and_b64 vcc, exec, s[14:15]
	s_cbranch_vccz .LBB0_431
	s_add_u32 s16, s1, s12
	s_addc_u32 s17, s5, s13
	s_add_u32 s16, s16, 0x10000180
	s_addc_u32 s17, s17, 0
	s_add_u32 m0, s98, 0x8000
	global_load_lds_dwordx4 v196, s[16:17]
	s_add_u32 m0, s98, 0xa000
	global_load_lds_dwordx4 v198, s[16:17]
	s_mov_b64 s[16:17], 0
.LBB0_431:
	s_andn2_b64 vcc, exec, s[16:17]
	s_cbranch_vccnz .LBB0_433
	s_add_i32 s62, s26, -5
	s_lshl_b64 s[16:17], s[62:63], 7
	s_add_u32 s16, s20, s16
	s_addc_u32 s17, s21, s17
	s_add_u32 m0, s98, 0x8000
	global_load_lds_dwordx4 v224, s[16:17]
	s_add_u32 m0, s98, 0xa000
	global_load_lds_dwordx4 v222, s[16:17]
.LBB0_433:
	s_setprio 1
	s_barrier
	s_waitcnt lgkmcnt(0)
	v_mfma_f32_16x16x32_bf16 v[62:65], v[130:133], v[186:189], v[62:65]
	v_mfma_f32_16x16x32_bf16 v[58:61], v[138:141], v[186:189], v[58:61]
	v_mfma_f32_16x16x32_bf16 v[54:57], v[130:133], v[178:181], v[54:57]
	v_mfma_f32_16x16x32_bf16 v[50:53], v[138:141], v[178:181], v[50:53]
	v_mfma_f32_16x16x32_bf16 v[46:49], v[130:133], v[170:173], v[46:49]
	v_mfma_f32_16x16x32_bf16 v[42:45], v[138:141], v[170:173], v[42:45]
	v_mfma_f32_16x16x32_bf16 v[38:41], v[130:133], v[162:165], v[38:41]
	v_mfma_f32_16x16x32_bf16 v[34:37], v[138:141], v[162:165], v[34:37]
	v_mfma_f32_16x16x32_bf16 v[62:65], v[134:137], v[190:193], v[62:65]
	v_mfma_f32_16x16x32_bf16 v[58:61], v[142:145], v[190:193], v[58:61]
	v_mfma_f32_16x16x32_bf16 v[54:57], v[134:137], v[182:185], v[54:57]
	v_mfma_f32_16x16x32_bf16 v[50:53], v[142:145], v[182:185], v[50:53]
	v_mfma_f32_16x16x32_bf16 v[46:49], v[134:137], v[174:177], v[46:49]
	v_mfma_f32_16x16x32_bf16 v[42:45], v[142:145], v[174:177], v[42:45]
	v_mfma_f32_16x16x32_bf16 v[38:41], v[134:137], v[166:169], v[38:41]
	v_mfma_f32_16x16x32_bf16 v[34:37], v[142:145], v[166:169], v[34:37]
	s_barrier
	s_setprio 0
	s_mov_b64 s[16:17], -1
	s_and_b64 vcc, exec, s[14:15]
	s_cbranch_vccz .LBB0_435
	s_add_u32 s14, s24, s12
	s_addc_u32 s15, s25, s13
	s_add_u32 s14, s14, 0x2e20180
	s_addc_u32 s15, s15, 0
	s_add_u32 m0, s98, 0x1c000
	global_load_lds_dwordx4 v200, s[14:15]
	s_add_u32 m0, s98, 0x1e000
	global_load_lds_dwordx4 v202, s[14:15]
	s_mov_b64 s[16:17], 0
.LBB0_435:
	s_andn2_b64 vcc, exec, s[16:17]
	s_cbranch_vccnz .LBB0_437
	s_add_i32 s62, s26, -5
	s_lshl_b64 s[14:15], s[62:63], 7
	s_add_u32 s14, s22, s14
	s_addc_u32 s15, s23, s15
	s_add_u32 s14, s14, 0x40000
	s_addc_u32 s15, s15, 0
	s_add_u32 m0, s98, 0x1c000
	global_load_lds_dwordx4 v232, s[14:15]
	s_add_u32 m0, s98, 0x1e000
	global_load_lds_dwordx4 v234, s[14:15]
